# grid barrier: acquire invalidate (buffer_inv sc1) issued at arrival, overlapped with the wait, instead of after the flag
# speedup vs baseline: 1.0135x; 1.0135x over previous
.LBB0_595:
	s_or_b64 exec, exec, s[4:5]
	v_cvt_f32_u32_e32 v4, v2
	s_waitcnt vmcnt(0)
	v_readfirstlane_b32 s4, v3
	buffer_inv sc1
	v_sub_u32_e32 v3, 0, v2
	v_rcp_iflag_f32_e32 v4, v4
	v_add_u32_e32 v5, s4, v1
	v_mul_f32_e32 v4, 0x4f7ffffe, v4
	v_cvt_u32_f32_e32 v4, v4
	v_mul_lo_u32 v1, v3, v4
	v_mul_hi_u32 v1, v4, v1
	v_add_u32_e32 v1, v4, v1
	v_mul_hi_u32 v1, v5, v1
	v_mul_lo_u32 v3, v1, v2
	v_sub_u32_e32 v3, v5, v3
	v_add_u32_e32 v4, 1, v1
	v_cmp_ge_u32_e32 vcc, v3, v2
	s_nop 1
	v_cndmask_b32_e32 v1, v1, v4, vcc
	v_sub_u32_e32 v4, v3, v2
	v_cndmask_b32_e32 v3, v3, v4, vcc
	v_add_u32_e32 v4, 1, v1
	v_cmp_ge_u32_e32 vcc, v3, v2
	v_add_u32_e32 v3, 1, v5
	s_nop 0
	v_cndmask_b32_e32 v1, v1, v4, vcc
	v_mul_lo_u32 v4, v2, v1
	v_add_u32_e32 v2, v4, v2
	v_cmp_ne_u32_e32 vcc, v3, v2
	s_and_saveexec_b64 s[4:5], vcc
	s_xor_b64 s[4:5], exec, s[4:5]
	s_cbranch_execz .LBB0_609
	v_readlane_b32 s6, v254, 38
	v_readlane_b32 s7, v254, 39
	s_waitcnt lgkmcnt(0)
	s_nop 3
	global_load_dword v0, v81, s[6:7] sc1
	s_waitcnt vmcnt(0)
	v_cmp_eq_u32_e32 vcc, v0, v1
	s_and_saveexec_b64 s[6:7], vcc
	s_cbranch_execz .LBB0_608
	s_mov_b64 s[26:27], s[22:23]
	s_mov_b32 s18, 1
	s_mov_b64 s[8:9], 0
	s_branch .LBB0_599

.LBB0_608:
	s_or_b64 exec, exec, s[6:7]
	s_waitcnt vmcnt(0)
	s_nop 0
	s_waitcnt vmcnt(0)

.LBB0_626:
	s_or_b64 exec, exec, s[4:5]
	s_mov_b64 s[4:5], exec
	v_mbcnt_lo_u32_b32 v0, s4, 0
	v_mbcnt_hi_u32_b32 v0, s5, v0
	v_cmp_eq_u32_e32 vcc, 0, v0
	s_waitcnt vmcnt(0)
	s_nop 0
	s_and_saveexec_b64 s[6:7], vcc
	s_cbranch_execz .LBB0_21
	s_bcnt1_i32_b64 s4, s[4:5]
	v_mov_b32_e32 v0, s4
	v_readlane_b32 s4, v254, 38
	v_readlane_b32 s5, v254, 39
	s_nop 4
	global_atomic_add v81, v0, s[4:5]
	s_branch .LBB0_21
